# same as previous plus a 4-byte entry pad to test code placement sensitivity
# speedup vs baseline: 1.0037x; 1.0037x over previous
_Z4mega6Params:
	s_nop 0
	s_load_dwordx2 s[90:91], s[0:1], 0x140
	v_writelane_b32 v251, s2, 0
	s_add_u32 s2, s0, 0x140
	v_writelane_b32 v251, s0, 1
	s_addc_u32 s3, s1, 0
	v_and_b32_e32 v224, 0x3ff, v0
	v_writelane_b32 v251, s1, 2
	v_writelane_b32 v251, s2, 3
	v_cmp_eq_u32_e64 s[0:1], 0, v224
	s_nop 0
	v_writelane_b32 v251, s3, 4
	v_writelane_b32 v251, s0, 5
	s_nop 1
	v_writelane_b32 v251, s1, 6
	s_and_saveexec_b64 s[2:3], s[0:1]
	s_cbranch_execz .LBB0_2
	s_add_i32 s4, 0, 0x27fe0
	v_mov_b32_e32 v1, 0
	v_mov_b32_e32 v2, s4
	s_add_i32 s4, 0, 0x27fe4
	ds_write_b32 v2, v1
	v_mov_b32_e32 v2, s4
	ds_write_b32 v2, v1
